# P0: the hoisted RMSNorm row loads now issue at the very start of P0 (before the table-building branch), so the 98 table-building waves stream x while they build tables
# baseline (speedup 1.0000x reference)
.LBB0_13:
	s_or_b64 exec, exec, s[4:5]
	s_load_dwordx4 s[4:7], s[0:1], 0xe0
	s_lshr_b32 s2, s82, 6
	v_and_b32_e32 v228, 63, v0
	s_load_dwordx2 s[98:99], s[0:1], 0x0
	s_lshl_b32 s100, s83, 3
	s_add_i32 s100, s100, s2
	s_lshl_b32 s101, s100, 12
	v_lshlrev_b32_e32 v130, 4, v228
	s_waitcnt lgkmcnt(0)
	s_add_u32 s98, s98, s101
	s_addc_u32 s99, s99, 0
	s_add_u32 s98, s98, 0x800000
	s_addc_u32 s99, s99, 0
	global_load_dwordx4 v[106:109], v130, s[98:99] nt
	global_load_dwordx4 v[94:97], v130, s[98:99] offset:1024 nt
	global_load_dwordx4 v[86:89], v130, s[98:99] offset:2048 nt
	global_load_dwordx4 v[90:93], v130, s[98:99] offset:3072 nt
	s_add_u32 s98, s98, 0x800000
	s_addc_u32 s99, s99, 0
	global_load_dwordx4 v[126:129], v130, s[98:99] nt
	global_load_dwordx4 v[122:125], v130, s[98:99] offset:1024 nt
	global_load_dwordx4 v[118:121], v130, s[98:99] offset:2048 nt
	global_load_dwordx4 v[114:117], v130, s[98:99] offset:3072 nt
	s_add_u32 s98, s98, 0x800000
	s_addc_u32 s99, s99, 0
	global_load_dwordx4 v[110:113], v130, s[98:99] nt
	global_load_dwordx4 v[102:105], v130, s[98:99] offset:1024 nt
	global_load_dwordx4 v[98:101], v130, s[98:99] offset:2048 nt
	global_load_dwordx4 v[82:85], v130, s[98:99] offset:3072 nt
	s_add_u32 s98, s98, 0x800000
	s_addc_u32 s99, s99, 0
	global_load_dwordx4 v[78:81], v130, s[98:99] nt
	global_load_dwordx4 v[74:77], v130, s[98:99] offset:1024 nt
	global_load_dwordx4 v[70:73], v130, s[98:99] offset:2048 nt
	s_cmp_lg_u32 s2, 7
	v_writelane_b32 v252, s2, 47
	s_waitcnt lgkmcnt(0)
	s_mov_b64 s[12:13], s[6:7]
	s_cbranch_scc1 .LBB0_48
	s_load_dword s3, s[0:1], 0xf8
	s_not_b32 s2, s83
	s_waitcnt lgkmcnt(0)
	s_add_i32 s2, s3, s2
	s_cmpk_gt_i32 s2, 0x61
	s_cbranch_scc1 .LBB0_48
	s_mov_b64 s[8:9], -1
	s_mov_b64 s[4:5], 0
	s_cmp_lt_i32 s2, 1
	s_mov_b64 s[6:7], 0
	s_cbranch_scc1 .LBB0_21
	s_cmp_eq_u32 s2, 1
	s_mov_b64 s[6:7], -1
	s_cbranch_scc0 .LBB0_27
	v_and_b32_e32 v1, 63, v0
	v_lshlrev_b32_e32 v2, 2, v1
	v_mov_b32_e32 v3, 0
	v_lshl_add_u64 v[4:5], s[12:13], 0, v[2:3]
	s_mov_b64 s[6:7], 0xb00100
	v_lshl_add_u64 v[4:5], v[4:5], 0, s[6:7]
	s_mov_b64 s[6:7], 0
	s_movk_i32 s3, 0x42
	s_movk_i32 s14, 0x4c
	s_movk_i32 s15, 0x56
	s_movk_i32 s16, 0x62
	s_movk_i32 s17, 0x70
	s_mov_b64 s[8:9], 0x100
	s_movk_i32 s18, 0x1bf
	v_mov_b32_e32 v1, 0
	v_mov_b32_e32 v6, v228
	s_branch .LBB0_19
